# gemm8 LDS tiles: 16-B chunk parity swizzle for rows 4..11 of each 16-row group (ds_read_b128 lane-group conflicts), on top of v40
# speedup vs baseline: 1.0480x; 1.0264x over previous
.LBB0_189:
	s_cmp_lt_i32 s88, 3
	s_cselect_b64 s[18:19], -1, 0
	s_and_b64 s[4:5], s[18:19], s[4:5]
	s_andn2_b64 vcc, exec, s[4:5]
	s_cbranch_vccnz .LBB0_426
	s_add_u32 s16, s34, 0x28c4000
	s_addc_u32 s17, s35, 0
	s_add_u32 s6, s34, 0x8a44000
	s_addc_u32 s7, s35, 0
	s_add_u32 s8, s0, 0x120
	s_addc_u32 s9, s1, 0
	s_cmpk_lt_i32 s2, 0x100
	s_cbranch_scc0 .LBB0_197
	s_lshl_b32 s4, s2, 5
	s_and_b32 s4, s4, 0xe0
	s_ashr_i32 s5, s2, 3
	s_add_i32 s4, s4, s5
	s_ashr_i32 s5, s4, 31
	s_lshr_b32 s5, s5, 26
	s_add_i32 s5, s4, s5
	s_and_b32 s8, s5, 0xffffffc0
	s_sub_i32 s4, s4, s8
	s_ashr_i32 s8, s4, 31
	s_lshr_b32 s8, s8, 29
	s_add_i32 s8, s4, s8
	s_and_b32 s9, s8, 0xfffff8
	s_sub_i32 s4, s4, s9
	s_lshl_b32 s5, s5, 5
	s_and_b32 s5, s5, 0xfffff800
	s_lshl_b32 s4, s4, 8
	s_add_i32 s26, s4, s5
	v_mov_b32_e32 v65, v204
	s_lshl_b32 s4, s8, 5
	s_ashr_i32 s27, s26, 31
	s_and_b32 s28, s4, 0xffffff00
	s_lshl_b64 s[4:5], s[26:27], 11
	v_lshlrev_b32_e32 v0, 4, v65
	v_ashrrev_i32_e32 v67, 3, v65
	s_add_u32 s4, s6, s4
	v_and_b32_e32 v64, 0x70, v0
	s_addc_u32 s5, s7, s5
	v_lshl_or_b32 v192, v67, 11, v64
	v_mov_b32_e32 v193, 0
	v_lshl_add_u64 v[0:1], s[4:5], 0, v[192:193]
	s_mov_b32 s14, 0x20000
	v_add_co_u32_e32 v2, vcc, s14, v0
	s_ashr_i32 s29, s28, 31
	s_nop 0
	v_addc_co_u32_e32 v3, vcc, 0, v1, vcc
	s_mov_b32 s15, 0x40000
	s_lshl_b64 s[8:9], s[28:29], 11
	v_add_co_u32_e32 v12, vcc, s15, v0
	s_add_u32 s30, s34, s8
	s_nop 0
	v_addc_co_u32_e32 v13, vcc, 0, v1, vcc
	s_mov_b32 s27, 0x60000
	s_addc_u32 s31, s35, s9
	global_load_dwordx4 v[32:35], v192, s[4:5]
	global_load_dwordx4 v[48:51], v192, s[30:31]
	v_add_co_u32_e32 v0, vcc, s27, v0
	global_load_dwordx4 v[36:39], v[2:3], off
	s_nop 0
	v_addc_co_u32_e32 v1, vcc, 0, v1, vcc
	v_lshl_add_u64 v[4:5], s[30:31], 0, v[192:193]
	global_load_dwordx4 v[40:43], v[12:13], off
	v_add_co_u32_e32 v20, vcc, s14, v4
	global_load_dwordx4 v[44:47], v[0:1], off
	s_nop 0
	v_addc_co_u32_e32 v21, vcc, 0, v5, vcc
	v_add_co_u32_e32 v24, vcc, s15, v4
	global_load_dwordx4 v[52:55], v[20:21], off
	s_nop 0
	v_addc_co_u32_e32 v25, vcc, 0, v5, vcc
	global_load_dwordx4 v[56:59], v[24:25], off
	v_add_co_u32_e32 v28, vcc, s27, v4
	v_ashrrev_i32_e32 v66, 1, v65
	s_nop 0
	v_addc_co_u32_e32 v29, vcc, 0, v5, vcc
	global_load_dwordx4 v[60:63], v[28:29], off
	global_load_dwordx4 v[4:7], v192, s[4:5] offset:128
	global_load_dwordx4 v[8:11], v[2:3], off offset:128
	s_nop 0
	global_load_dwordx4 v[12:15], v[12:13], off offset:128
	s_nop 0
	global_load_dwordx4 v[16:19], v[0:1], off offset:128
	s_nop 0
	global_load_dwordx4 v[0:3], v192, s[30:31] offset:128
	s_nop 0
	global_load_dwordx4 v[20:23], v[20:21], off offset:128
	s_nop 0
	global_load_dwordx4 v[24:27], v[24:25], off offset:128
	s_nop 0
	global_load_dwordx4 v[28:31], v[28:29], off offset:128
	s_movk_i32 s10, 0x90
	v_bfe_u32 v68, v65, 4, 2
	v_and_b32_e32 v69, 0xffffff80, v66
	v_lshlrev_b32_e32 v66, 4, v68
	v_lshrrev_b32_e32 v159, 1, v65
	v_xor_b32_e32 v158, v65, v159
	v_bfe_u32 v158, v158, 2, 1
	v_bfe_u32 v159, v65, 4, 1
	v_and_b32_e32 v159, v159, v158
	v_lshlrev_b32_e32 v159, 5, v159
	v_lshlrev_b32_e32 v158, 4, v158
	v_sub_u32_e32 v158, v158, v159
	v_add_u32_e32 v66, v66, v158
	v_lshrrev_b32_e32 v158, 3, v65
	v_lshrrev_b32_e32 v159, 1, v158
	v_xor_b32_e32 v158, v158, v159
	v_bfe_u32 v158, v158, 2, 1
	v_and_b32_e32 v159, v158, v65
	v_lshlrev_b32_e32 v159, 5, v159
	v_lshlrev_b32_e32 v158, 4, v158
	v_sub_u32_e32 v158, v158, v159
	v_add_u32_e32 v64, v64, v158
	v_mad_u64_u32 v[194:195], s[8:9], v67, s10, v[64:65]
	v_and_or_b32 v64, v65, 15, v69
	v_add_u32_e32 v195, 0x12000, v194
	v_mad_u64_u32 v[196:197], s[8:9], v64, s10, v[66:67]
	v_and_b32_e32 v197, 0xcf, v65
	s_add_u32 s8, s0, 0x120
	s_addc_u32 s9, s1, 0
	v_add_u32_e32 v199, 0x1b000, v194
	v_lshl_or_b32 v201, v68, 2, v69
	s_movk_i32 s33, 0x1040
	s_mov_b32 s42, s2
	s_mov_b64 s[10:11], s[4:5]
	s_mov_b64 s[12:13], s[30:31]
	s_waitcnt vmcnt(15)
	ds_write_b128 v194, v[32:35]
	s_waitcnt vmcnt(13)
	ds_write_b128 v194, v[36:39] offset:9216
	s_waitcnt vmcnt(12)
	ds_write_b128 v194, v[40:43] offset:18432
	s_waitcnt vmcnt(11)
	ds_write_b128 v194, v[44:47] offset:27648
	ds_write_b128 v195, v[48:51]
	s_waitcnt vmcnt(10)
	ds_write_b128 v195, v[52:55] offset:9216
	s_waitcnt vmcnt(9)
	ds_write_b128 v195, v[56:59] offset:18432
	s_waitcnt vmcnt(8)
	ds_write_b128 v195, v[60:63] offset:27648
	s_waitcnt lgkmcnt(0)
	s_barrier
	s_load_dword s29, s[0:1], 0x120
	v_mul_u32_u24_e32 v32, 0x48, v197
	v_lshl_add_u32 v32, v32, 1, v66
	v_add_u32_e32 v198, 0x12000, v32
	v_add_u32_e32 v200, 0x1b000, v32

.LBB0_1014:
	s_cmp_lt_i32 s88, 8
	s_cselect_b64 s[4:5], -1, 0
	s_and_b64 s[6:7], s[4:5], s[6:7]
	s_andn2_b64 vcc, exec, s[6:7]
	s_cbranch_vccnz .LBB0_1023
	s_cmpk_gt_i32 s2, 0xff
	s_cbranch_scc1 .LBB0_1023
	s_add_u32 s14, s34, 0x9a44000
	s_addc_u32 s15, s35, 0
	s_add_u32 s33, s34, 0x520000
	s_waitcnt lgkmcnt(0)
	s_addc_u32 s62, s35, 0
	s_lshl_b32 s6, s2, 5
	s_and_b32 s6, s6, 0xe0
	s_ashr_i32 s7, s2, 3
	s_add_i32 s6, s6, s7
	s_ashr_i32 s56, s6, 7
	s_lshl_b32 s6, s6, 6
	s_and_b32 s76, s6, 0x1f00
	s_lshl_b32 s6, s7, 8
	s_and_b32 s75, s6, 0x300
	s_lshl_b32 s6, s76, 11
	s_add_u32 s8, s14, s6
	v_mov_b32_e32 v65, v204
	s_addc_u32 s9, s15, 0
	s_ashr_i32 s57, s56, 31
	s_lshl_b64 s[6:7], s[56:57], 10
	s_waitcnt vmcnt(7)
	v_lshlrev_b32_e32 v0, 4, v65
	v_ashrrev_i32_e32 v78, 3, v65
	s_add_u32 s58, s8, s6
	v_and_b32_e32 v64, 0x70, v0
	v_mov_b32_e32 v199, 0
	s_addc_u32 s59, s9, s7
	v_lshl_or_b32 v196, v78, 11, v64
	v_mov_b32_e32 v197, v199
	v_lshl_add_u64 v[0:1], s[58:59], 0, v[196:197]
	s_mov_b32 s57, 0x20000
	s_lshl_b32 s8, s75, 11
	v_add_co_u32_e32 v66, vcc, s57, v0
	s_add_u32 s8, s33, s8
	s_nop 0
	v_addc_co_u32_e32 v67, vcc, 0, v1, vcc
	s_mov_b32 s63, 0x40000
	s_addc_u32 s9, s62, 0
	v_add_co_u32_e32 v68, vcc, s63, v0
	s_add_u32 s60, s8, s6
	s_nop 0
	v_addc_co_u32_e32 v69, vcc, 0, v1, vcc
	s_mov_b32 s64, 0x60000
	s_addc_u32 s61, s9, s7
	global_load_dwordx4 v[32:35], v196, s[58:59]
	global_load_dwordx4 v[48:51], v196, s[60:61]
	v_add_co_u32_e32 v70, vcc, s64, v0
	global_load_dwordx4 v[36:39], v[66:67], off
	global_load_dwordx4 v[40:43], v[68:69], off
	v_addc_co_u32_e32 v71, vcc, 0, v1, vcc
	v_lshl_add_u64 v[0:1], s[60:61], 0, v[196:197]
	v_add_co_u32_e32 v72, vcc, s57, v0
	global_load_dwordx4 v[44:47], v[70:71], off
	s_nop 0
	v_addc_co_u32_e32 v73, vcc, 0, v1, vcc
	v_add_co_u32_e32 v74, vcc, s63, v0
	global_load_dwordx4 v[52:55], v[72:73], off
	s_nop 0
	v_addc_co_u32_e32 v75, vcc, 0, v1, vcc
	global_load_dwordx4 v[56:59], v[74:75], off
	v_add_co_u32_e32 v76, vcc, s64, v0
	s_movk_i32 s8, 0x90
	s_nop 0
	v_addc_co_u32_e32 v77, vcc, 0, v1, vcc
	global_load_dwordx4 v[60:63], v[76:77], off
	global_load_dwordx4 v[4:7], v196, s[58:59] offset:128
	global_load_dwordx4 v[8:11], v[66:67], off offset:128
	global_load_dwordx4 v[12:15], v[68:69], off offset:128
	global_load_dwordx4 v[16:19], v[70:71], off offset:128
	global_load_dwordx4 v[0:3], v196, s[60:61] offset:128
	global_load_dwordx4 v[20:23], v[72:73], off offset:128
	global_load_dwordx4 v[24:27], v[74:75], off offset:128
	global_load_dwordx4 v[28:31], v[76:77], off offset:128
	v_ashrrev_i32_e32 v66, 1, v65
	v_bfe_u32 v67, v65, 4, 2
	v_and_b32_e32 v206, 0xcf, v65
	v_and_b32_e32 v68, 0xffffff80, v66
	v_lshrrev_b32_e32 v158, 3, v65
	v_lshrrev_b32_e32 v159, 1, v158
	v_xor_b32_e32 v158, v158, v159
	v_bfe_u32 v158, v158, 2, 1
	v_and_b32_e32 v159, v158, v65
	v_lshlrev_b32_e32 v159, 5, v159
	v_lshlrev_b32_e32 v158, 4, v158
	v_sub_u32_e32 v158, v158, v159
	v_add_u32_e32 v64, v64, v158
	v_mad_u64_u32 v[200:201], s[6:7], v78, s8, v[64:65]
	v_lshlrev_b32_e32 v66, 4, v67
	v_lshrrev_b32_e32 v159, 1, v65
	v_xor_b32_e32 v158, v65, v159
	v_bfe_u32 v158, v158, 2, 1
	v_bfe_u32 v159, v65, 4, 1
	v_and_b32_e32 v159, v159, v158
	v_lshlrev_b32_e32 v159, 5, v159
	v_lshlrev_b32_e32 v158, 4, v158
	v_sub_u32_e32 v158, v158, v159
	v_add_u32_e32 v66, v66, v158
	v_and_or_b32 v64, v65, 15, v68
	v_add_u32_e32 v207, 0x12000, v200
	v_mad_u64_u32 v[202:203], s[6:7], v64, s8, v[66:67]
	v_lshl_or_b32 v201, v67, 2, v68
	v_add_u32_e32 v208, 0x1b000, v200
	s_mov_b64 s[6:7], 0x20800
	s_mov_b64 s[8:9], 0x21000
	s_mov_b32 s65, 0x21000
	s_mov_b64 s[10:11], 0x21800
	s_mov_b64 s[12:13], 0x28000
	s_mov_b32 s66, 0x28000
	s_mov_b64 s[16:17], 0x28800
	s_mov_b64 s[18:19], 0x29000
	s_mov_b32 s67, 0x29000
	s_mov_b64 s[20:21], 0x29800
	s_mov_b64 s[22:23], 0x30000
	s_mov_b32 s68, 0x30000
	s_mov_b64 s[24:25], 0x30800
	s_mov_b64 s[26:27], 0x31000
	s_mov_b32 s69, 0x31000
	s_waitcnt vmcnt(15)
	ds_write_b128 v200, v[32:35]
	s_waitcnt vmcnt(13)
	ds_write_b128 v200, v[36:39] offset:9216
	s_waitcnt vmcnt(12)
	ds_write_b128 v200, v[40:43] offset:18432
	s_waitcnt vmcnt(11)
	ds_write_b128 v200, v[44:47] offset:27648
	ds_write_b128 v207, v[48:51]
	s_waitcnt vmcnt(10)
	ds_write_b128 v207, v[52:55] offset:9216
	s_waitcnt vmcnt(9)
	ds_write_b128 v207, v[56:59] offset:18432
	s_waitcnt vmcnt(8)
	ds_write_b128 v207, v[60:63] offset:27648
	v_mul_u32_u24_e32 v32, 0x48, v206
	v_lshl_add_u32 v32, v32, 1, v66
	v_add_u32_e32 v203, 0x12000, v32
	v_add_u32_e32 v209, 0x1b000, v32
	s_mov_b64 s[28:29], 0x31800
	s_mov_b64 s[30:31], 0x38000
	s_mov_b32 s70, 0x38000
	s_mov_b64 s[36:37], 0x38800
	s_mov_b64 s[38:39], 0x39000
	s_mov_b32 s71, 0x39000
	s_mov_b64 s[40:41], 0x39800
	s_mov_b32 s72, s2
	s_mov_b64 s[42:43], s[58:59]
	s_mov_b64 s[44:45], s[60:61]
	s_waitcnt lgkmcnt(0)
	s_barrier

.LBB0_1140:
	s_cmp_lt_i32 s88, 10
	s_cselect_b64 s[6:7], -1, 0
	s_and_b64 s[4:5], s[6:7], s[4:5]
	s_andn2_b64 vcc, exec, s[4:5]
	s_cbranch_vccnz .LBB0_1148
	s_cmpk_gt_i32 s2, 0x2bf
	s_cbranch_scc1 .LBB0_1148
	s_add_u32 s8, s34, 0x28c4000
	s_addc_u32 s9, s35, 0
	s_add_u32 s14, s34, 0x8a44000
	s_addc_u32 s15, s35, 0
	s_add_u32 s28, s34, 0x7a0000
	s_addc_u32 s29, s35, 0
	s_and_b32 s4, s2, 7
	s_mulk_i32 s4, 0x58
	s_ashr_i32 s5, s2, 3
	s_add_i32 s4, s4, s5
	s_mul_hi_i32 s5, s4, 0x2e8ba2e9
	s_lshr_b32 s10, s5, 31
	s_ashr_i32 s5, s5, 5
	s_add_i32 s5, s5, s10
	s_mul_i32 s10, s5, 0xffffff50
	s_add_i32 s4, s10, s4
	s_ashr_i32 s10, s4, 31
	s_lshr_b32 s10, s10, 29
	s_add_i32 s10, s4, s10
	s_and_b32 s11, s10, 0xfffff8
	s_sub_i32 s4, s4, s11
	s_lshl_b32 s5, s5, 11
	s_lshl_b32 s4, s4, 8
	s_add_i32 s22, s4, s5
	v_mov_b32_e32 v65, v204
	s_lshl_b32 s4, s10, 5
	s_ashr_i32 s23, s22, 31
	s_and_b32 s24, s4, 0xffffff00
	s_lshl_b64 s[4:5], s[22:23], 11
	s_waitcnt vmcnt(7)
	v_lshlrev_b32_e32 v0, 4, v65
	v_ashrrev_i32_e32 v78, 3, v65
	s_add_u32 s4, s14, s4
	v_and_b32_e32 v64, 0x70, v0
	s_addc_u32 s5, s15, s5
	v_lshl_or_b32 v192, v78, 11, v64
	v_mov_b32_e32 v193, 0
	v_lshl_add_u64 v[0:1], s[4:5], 0, v[192:193]
	s_mov_b32 s23, 0x20000
	s_ashr_i32 s25, s24, 31
	v_add_co_u32_e32 v66, vcc, s23, v0
	s_lshl_b64 s[10:11], s[24:25], 11
	s_nop 0
	v_addc_co_u32_e32 v67, vcc, 0, v1, vcc
	s_mov_b32 s25, 0x40000
	v_add_co_u32_e32 v68, vcc, s25, v0
	s_add_u32 s26, s28, s10
	s_nop 0
	v_addc_co_u32_e32 v69, vcc, 0, v1, vcc
	s_mov_b32 s30, 0x60000
	s_addc_u32 s27, s29, s11
	global_load_dwordx4 v[32:35], v192, s[4:5]
	global_load_dwordx4 v[48:51], v192, s[26:27]
	v_add_co_u32_e32 v70, vcc, s30, v0
	global_load_dwordx4 v[36:39], v[66:67], off
	global_load_dwordx4 v[40:43], v[68:69], off
	v_addc_co_u32_e32 v71, vcc, 0, v1, vcc
	v_lshl_add_u64 v[0:1], s[26:27], 0, v[192:193]
	v_add_co_u32_e32 v72, vcc, s23, v0
	global_load_dwordx4 v[44:47], v[70:71], off
	s_nop 0
	v_addc_co_u32_e32 v73, vcc, 0, v1, vcc
	v_add_co_u32_e32 v74, vcc, s25, v0
	global_load_dwordx4 v[52:55], v[72:73], off
	s_nop 0
	v_addc_co_u32_e32 v75, vcc, 0, v1, vcc
	global_load_dwordx4 v[56:59], v[74:75], off
	v_add_co_u32_e32 v76, vcc, s30, v0
	s_movk_i32 s12, 0x90
	s_nop 0
	v_addc_co_u32_e32 v77, vcc, 0, v1, vcc
	global_load_dwordx4 v[60:63], v[76:77], off
	global_load_dwordx4 v[4:7], v192, s[4:5] offset:128
	global_load_dwordx4 v[8:11], v[66:67], off offset:128
	global_load_dwordx4 v[12:15], v[68:69], off offset:128
	global_load_dwordx4 v[16:19], v[70:71], off offset:128
	global_load_dwordx4 v[0:3], v192, s[26:27] offset:128
	global_load_dwordx4 v[20:23], v[72:73], off offset:128
	global_load_dwordx4 v[24:27], v[74:75], off offset:128
	global_load_dwordx4 v[28:31], v[76:77], off offset:128
	v_lshrrev_b32_e32 v158, 3, v65
	v_lshrrev_b32_e32 v159, 1, v158
	v_xor_b32_e32 v158, v158, v159
	v_bfe_u32 v158, v158, 2, 1
	v_and_b32_e32 v159, v158, v65
	v_lshlrev_b32_e32 v159, 5, v159
	v_lshlrev_b32_e32 v158, 4, v158
	v_sub_u32_e32 v158, v158, v159
	v_add_u32_e32 v64, v64, v158
	v_mad_u64_u32 v[194:195], s[10:11], v78, s12, v[64:65]
	v_ashrrev_i32_e32 v66, 1, v65
	v_add_u32_e32 v195, 0x12000, v194
	v_bfe_u32 v67, v65, 4, 2
	v_and_b32_e32 v198, 0xcf, v65
	v_and_b32_e32 v68, 0xffffff80, v66
	v_lshlrev_b32_e32 v66, 4, v67
	v_lshrrev_b32_e32 v159, 1, v65
	v_xor_b32_e32 v158, v65, v159
	v_bfe_u32 v158, v158, 2, 1
	v_bfe_u32 v159, v65, 4, 1
	v_and_b32_e32 v159, v159, v158
	v_lshlrev_b32_e32 v159, 5, v159
	v_lshlrev_b32_e32 v158, 4, v158
	v_sub_u32_e32 v158, v158, v159
	v_add_u32_e32 v66, v66, v158
	v_and_or_b32 v64, v65, 15, v68
	v_mad_u64_u32 v[196:197], s[10:11], v64, s12, v[66:67]
	v_add_u32_e32 v199, 0x1b000, v194
	v_lshl_or_b32 v201, v67, 2, v68
	s_movk_i32 s33, 0x1600
	s_waitcnt lgkmcnt(0)
	s_mov_b32 s36, s2
	s_mov_b64 s[10:11], s[4:5]
	s_mov_b64 s[12:13], s[26:27]
	s_waitcnt vmcnt(15)
	ds_write_b128 v194, v[32:35]
	s_waitcnt vmcnt(13)
	ds_write_b128 v194, v[36:39] offset:9216
	s_waitcnt vmcnt(12)
	ds_write_b128 v194, v[40:43] offset:18432
	s_waitcnt vmcnt(11)
	ds_write_b128 v194, v[44:47] offset:27648
	ds_write_b128 v195, v[48:51]
	s_waitcnt vmcnt(10)
	ds_write_b128 v195, v[52:55] offset:9216
	s_waitcnt vmcnt(9)
	ds_write_b128 v195, v[56:59] offset:18432
	s_waitcnt vmcnt(8)
	ds_write_b128 v195, v[60:63] offset:27648
	s_waitcnt lgkmcnt(0)
	s_barrier
	s_load_dword s31, s[0:1], 0x120
	v_mul_u32_u24_e32 v32, 0x48, v198
	v_lshl_add_u32 v32, v32, 1, v66
	v_add_u32_e32 v197, 0x12000, v32
	v_add_u32_e32 v200, 0x1b000, v32

.LBB0_1202:
	s_cmp_lt_i32 s88, 11
	s_cselect_b64 s[4:5], -1, 0
	s_and_b64 s[6:7], s[4:5], s[8:9]
	s_andn2_b64 vcc, exec, s[6:7]
	s_cbranch_vccnz .LBB0_1211
	s_cmpk_gt_i32 s2, 0xff
	s_cbranch_scc1 .LBB0_1211
	s_add_u32 s14, s34, 0x28c4000
	s_addc_u32 s15, s35, 0
	s_add_u32 s33, s34, 0x1da0000
	s_waitcnt lgkmcnt(0)
	s_addc_u32 s56, s35, 0
	s_lshl_b32 s6, s2, 5
	s_and_b32 s6, s6, 0xe0
	s_ashr_i32 s7, s2, 3
	s_add_i32 s6, s6, s7
	s_ashr_i32 s72, s6, 7
	s_lshl_b32 s6, s6, 6
	s_and_b32 s74, s6, 0x1f00
	s_lshl_b32 s6, s7, 8
	v_mov_b32_e32 v76, v204
	s_and_b32 s73, s6, 0x300
	s_mul_i32 s6, s74, 0x1600
	s_add_u32 s6, s14, s6
	v_ashrrev_i32_e32 v77, 3, v76
	s_waitcnt vmcnt(7)
	v_lshlrev_b32_e32 v0, 3, v76
	s_movk_i32 s8, 0xb00
	v_and_b32_e32 v78, 56, v0
	s_addc_u32 s7, s15, 0
	s_mul_i32 s10, s72, 0xb00
	v_mul_lo_u32 v0, v77, s8
	s_mul_hi_i32 s9, s72, 0xb00
	s_add_u32 s52, s6, s10
	v_or_b32_e32 v0, v0, v78
	v_mov_b32_e32 v199, 0
	s_addc_u32 s53, s7, s9
	v_lshlrev_b32_e32 v196, 1, v0
	v_mov_b32_e32 v197, v199
	v_lshl_add_u64 v[0:1], s[52:53], 0, v[196:197]
	s_mov_b32 s57, 0x58000
	s_mul_i32 s6, s73, 0x1600
	v_add_co_u32_e32 v64, vcc, s57, v0
	s_add_u32 s6, s33, s6
	s_nop 0
	v_addc_co_u32_e32 v65, vcc, 0, v1, vcc
	s_mov_b32 s58, 0xb0000
	s_addc_u32 s7, s56, 0
	v_add_co_u32_e32 v66, vcc, s58, v0
	s_add_u32 s54, s6, s10
	s_nop 0
	v_addc_co_u32_e32 v67, vcc, 0, v1, vcc
	s_mov_b32 s59, 0x108000
	s_addc_u32 s55, s7, s9
	global_load_dwordx4 v[32:35], v196, s[52:53]
	global_load_dwordx4 v[48:51], v196, s[54:55]
	v_add_co_u32_e32 v68, vcc, s59, v0
	global_load_dwordx4 v[36:39], v[64:65], off
	global_load_dwordx4 v[40:43], v[66:67], off
	v_addc_co_u32_e32 v69, vcc, 0, v1, vcc
	v_lshl_add_u64 v[0:1], s[54:55], 0, v[196:197]
	v_add_co_u32_e32 v70, vcc, s57, v0
	global_load_dwordx4 v[44:47], v[68:69], off
	s_nop 0
	v_addc_co_u32_e32 v71, vcc, 0, v1, vcc
	v_add_co_u32_e32 v72, vcc, s58, v0
	global_load_dwordx4 v[52:55], v[70:71], off
	s_nop 0
	v_addc_co_u32_e32 v73, vcc, 0, v1, vcc
	global_load_dwordx4 v[56:59], v[72:73], off
	v_add_co_u32_e32 v74, vcc, s59, v0
	s_movk_i32 s6, 0x90
	s_nop 0
	v_addc_co_u32_e32 v75, vcc, 0, v1, vcc
	global_load_dwordx4 v[60:63], v[74:75], off
	global_load_dwordx4 v[4:7], v196, s[52:53] offset:128
	global_load_dwordx4 v[8:11], v[64:65], off offset:128
	global_load_dwordx4 v[12:15], v[66:67], off offset:128
	global_load_dwordx4 v[16:19], v[68:69], off offset:128
	global_load_dwordx4 v[0:3], v196, s[54:55] offset:128
	global_load_dwordx4 v[20:23], v[70:71], off offset:128
	global_load_dwordx4 v[24:27], v[72:73], off offset:128
	global_load_dwordx4 v[28:31], v[74:75], off offset:128
	v_ashrrev_i32_e32 v65, 1, v76
	v_mul_lo_u32 v66, v77, s6
	v_bfe_u32 v64, v76, 4, 2
	v_and_b32_e32 v65, 0xffffff80, v65
	v_lshl_add_u32 v202, v78, 1, v66
	v_lshrrev_b32_e32 v158, 3, v76
	v_lshrrev_b32_e32 v159, 1, v158
	v_xor_b32_e32 v158, v158, v159
	v_bfe_u32 v158, v158, 2, 1
	v_and_b32_e32 v159, v158, v76
	v_lshlrev_b32_e32 v159, 5, v159
	v_lshlrev_b32_e32 v158, 4, v158
	v_sub_u32_e32 v158, v158, v159
	v_add_u32_e32 v202, v202, v158
	v_add_u32_e32 v206, 0x12000, v202
	v_and_b32_e32 v207, 0xcf, v76
	v_lshl_or_b32 v203, v64, 2, v65
	v_add_u32_e32 v208, 0x1b000, v202
	s_mov_b32 s60, 0x20000
	s_mov_b64 s[8:9], 0x20800
	s_mov_b64 s[10:11], 0x21000
	s_mov_b32 s61, 0x21000
	s_mov_b64 s[12:13], 0x21800
	s_mov_b64 s[16:17], 0x28000
	s_mov_b32 s62, 0x28000
	s_mov_b64 s[18:19], 0x28800
	s_mov_b64 s[20:21], 0x29000
	s_mov_b32 s63, 0x29000
	s_mov_b64 s[22:23], 0x29800
	s_mov_b64 s[24:25], 0x30000
	s_mov_b32 s64, 0x30000
	s_mov_b64 s[26:27], 0x30800
	s_mov_b64 s[28:29], 0x31000
	s_waitcnt vmcnt(15)
	ds_write_b128 v202, v[32:35]
	s_waitcnt vmcnt(13)
	ds_write_b128 v202, v[36:39] offset:9216
	s_waitcnt vmcnt(12)
	ds_write_b128 v202, v[40:43] offset:18432
	s_waitcnt vmcnt(11)
	ds_write_b128 v202, v[44:47] offset:27648
	ds_write_b128 v206, v[48:51]
	s_waitcnt vmcnt(10)
	ds_write_b128 v206, v[52:55] offset:9216
	s_waitcnt vmcnt(9)
	ds_write_b128 v206, v[56:59] offset:18432
	s_waitcnt vmcnt(8)
	ds_write_b128 v206, v[60:63] offset:27648
	v_and_or_b32 v33, v76, 15, v65
	v_lshlrev_b32_e32 v32, 4, v64
	v_lshrrev_b32_e32 v159, 1, v76
	v_xor_b32_e32 v158, v76, v159
	v_bfe_u32 v158, v158, 2, 1
	v_bfe_u32 v159, v76, 4, 1
	v_and_b32_e32 v159, v159, v158
	v_lshlrev_b32_e32 v159, 5, v159
	v_lshlrev_b32_e32 v158, 4, v158
	v_sub_u32_e32 v158, v158, v159
	v_add_u32_e32 v32, v32, v158
	v_mad_u64_u32 v[200:201], s[6:7], v33, s6, v[32:33]
	v_mul_u32_u24_e32 v33, 0x48, v207
	v_lshl_add_u32 v32, v33, 1, v32
	v_add_u32_e32 v201, 0x12000, v32
	v_add_u32_e32 v209, 0x1b000, v32
	s_mov_b64 s[6:7], 0x20000
	s_mov_b32 s65, 0x31000
	s_mov_b64 s[30:31], 0x31800
	s_mov_b64 s[36:37], 0x38000
	s_mov_b32 s66, 0x38000
	s_mov_b64 s[38:39], 0x38800
	s_mov_b64 s[40:41], 0x39000
	s_mov_b32 s67, 0x39000
	s_mov_b64 s[42:43], 0x39800
	s_mov_b32 s68, s2
	s_mov_b64 s[44:45], s[52:53]
	s_mov_b64 s[48:49], s[54:55]
	s_waitcnt lgkmcnt(0)
	s_barrier

.LBB0_1443:
	s_cmp_lt_i32 s88, 16
	s_cselect_b64 s[6:7], -1, 0
	s_and_b64 s[4:5], s[6:7], s[4:5]
	s_andn2_b64 vcc, exec, s[4:5]
	s_cbranch_vccnz .LBB0_1451
	s_cmpk_gt_i32 s2, 0x2bf
	s_cbranch_scc1 .LBB0_1451
	s_add_u32 s8, s34, 0x28c4000
	s_addc_u32 s9, s35, 0
	s_add_u32 s14, s34, 0x8a44000
	s_addc_u32 s15, s35, 0
	s_add_u32 s28, s34, 0x12a0000
	s_addc_u32 s29, s35, 0
	s_and_b32 s4, s2, 7
	s_mulk_i32 s4, 0x58
	s_ashr_i32 s5, s2, 3
	s_add_i32 s4, s4, s5
	s_mul_hi_i32 s5, s4, 0x2e8ba2e9
	s_lshr_b32 s10, s5, 31
	s_ashr_i32 s5, s5, 5
	s_add_i32 s5, s5, s10
	s_mul_i32 s10, s5, 0xffffff50
	s_add_i32 s4, s10, s4
	s_ashr_i32 s10, s4, 31
	s_lshr_b32 s10, s10, 29
	s_add_i32 s10, s4, s10
	s_and_b32 s11, s10, 0xfffff8
	s_sub_i32 s4, s4, s11
	s_lshl_b32 s5, s5, 11
	s_lshl_b32 s4, s4, 8
	s_add_i32 s22, s4, s5
	v_mov_b32_e32 v65, v204
	s_lshl_b32 s4, s10, 5
	s_ashr_i32 s23, s22, 31
	s_and_b32 s24, s4, 0xffffff00
	s_lshl_b64 s[4:5], s[22:23], 11
	s_waitcnt vmcnt(7)
	v_lshlrev_b32_e32 v0, 4, v65
	v_ashrrev_i32_e32 v78, 3, v65
	s_add_u32 s4, s14, s4
	v_and_b32_e32 v64, 0x70, v0
	s_addc_u32 s5, s15, s5
	v_lshl_or_b32 v192, v78, 11, v64
	v_mov_b32_e32 v193, 0
	v_lshl_add_u64 v[0:1], s[4:5], 0, v[192:193]
	s_mov_b32 s23, 0x20000
	s_ashr_i32 s25, s24, 31
	v_add_co_u32_e32 v66, vcc, s23, v0
	s_lshl_b64 s[10:11], s[24:25], 11
	s_nop 0
	v_addc_co_u32_e32 v67, vcc, 0, v1, vcc
	s_mov_b32 s25, 0x40000
	v_add_co_u32_e32 v68, vcc, s25, v0
	s_add_u32 s26, s28, s10
	s_nop 0
	v_addc_co_u32_e32 v69, vcc, 0, v1, vcc
	s_mov_b32 s30, 0x60000
	s_addc_u32 s27, s29, s11
	global_load_dwordx4 v[32:35], v192, s[4:5]
	global_load_dwordx4 v[48:51], v192, s[26:27]
	v_add_co_u32_e32 v70, vcc, s30, v0
	global_load_dwordx4 v[36:39], v[66:67], off
	global_load_dwordx4 v[40:43], v[68:69], off
	v_addc_co_u32_e32 v71, vcc, 0, v1, vcc
	v_lshl_add_u64 v[0:1], s[26:27], 0, v[192:193]
	v_add_co_u32_e32 v72, vcc, s23, v0
	global_load_dwordx4 v[44:47], v[70:71], off
	s_nop 0
	v_addc_co_u32_e32 v73, vcc, 0, v1, vcc
	v_add_co_u32_e32 v74, vcc, s25, v0
	global_load_dwordx4 v[52:55], v[72:73], off
	s_nop 0
	v_addc_co_u32_e32 v75, vcc, 0, v1, vcc
	global_load_dwordx4 v[56:59], v[74:75], off
	v_add_co_u32_e32 v76, vcc, s30, v0
	s_movk_i32 s12, 0x90
	s_nop 0
	v_addc_co_u32_e32 v77, vcc, 0, v1, vcc
	global_load_dwordx4 v[60:63], v[76:77], off
	global_load_dwordx4 v[4:7], v192, s[4:5] offset:128
	global_load_dwordx4 v[8:11], v[66:67], off offset:128
	global_load_dwordx4 v[12:15], v[68:69], off offset:128
	global_load_dwordx4 v[16:19], v[70:71], off offset:128
	global_load_dwordx4 v[0:3], v192, s[26:27] offset:128
	global_load_dwordx4 v[20:23], v[72:73], off offset:128
	global_load_dwordx4 v[24:27], v[74:75], off offset:128
	global_load_dwordx4 v[28:31], v[76:77], off offset:128
	v_lshrrev_b32_e32 v158, 3, v65
	v_lshrrev_b32_e32 v159, 1, v158
	v_xor_b32_e32 v158, v158, v159
	v_bfe_u32 v158, v158, 2, 1
	v_and_b32_e32 v159, v158, v65
	v_lshlrev_b32_e32 v159, 5, v159
	v_lshlrev_b32_e32 v158, 4, v158
	v_sub_u32_e32 v158, v158, v159
	v_add_u32_e32 v64, v64, v158
	v_mad_u64_u32 v[194:195], s[10:11], v78, s12, v[64:65]
	v_ashrrev_i32_e32 v66, 1, v65
	v_add_u32_e32 v195, 0x12000, v194
	v_bfe_u32 v67, v65, 4, 2
	v_and_b32_e32 v198, 0xcf, v65
	v_and_b32_e32 v68, 0xffffff80, v66
	v_lshlrev_b32_e32 v66, 4, v67
	v_lshrrev_b32_e32 v159, 1, v65
	v_xor_b32_e32 v158, v65, v159
	v_bfe_u32 v158, v158, 2, 1
	v_bfe_u32 v159, v65, 4, 1
	v_and_b32_e32 v159, v159, v158
	v_lshlrev_b32_e32 v159, 5, v159
	v_lshlrev_b32_e32 v158, 4, v158
	v_sub_u32_e32 v158, v158, v159
	v_add_u32_e32 v66, v66, v158
	v_and_or_b32 v64, v65, 15, v68
	v_mad_u64_u32 v[196:197], s[10:11], v64, s12, v[66:67]
	v_add_u32_e32 v199, 0x1b000, v194
	v_lshl_or_b32 v201, v67, 2, v68
	s_movk_i32 s33, 0x1600
	s_waitcnt lgkmcnt(0)
	s_mov_b32 s36, s2
	s_mov_b64 s[10:11], s[4:5]
	s_mov_b64 s[12:13], s[26:27]
	s_waitcnt vmcnt(15)
	ds_write_b128 v194, v[32:35]
	s_waitcnt vmcnt(13)
	ds_write_b128 v194, v[36:39] offset:9216
	s_waitcnt vmcnt(12)
	ds_write_b128 v194, v[40:43] offset:18432
	s_waitcnt vmcnt(11)
	ds_write_b128 v194, v[44:47] offset:27648
	ds_write_b128 v195, v[48:51]
	s_waitcnt vmcnt(10)
	ds_write_b128 v195, v[52:55] offset:9216
	s_waitcnt vmcnt(9)
	ds_write_b128 v195, v[56:59] offset:18432
	s_waitcnt vmcnt(8)
	ds_write_b128 v195, v[60:63] offset:27648
	s_waitcnt lgkmcnt(0)
	s_barrier
	s_load_dword s31, s[0:1], 0x120
	v_mul_u32_u24_e32 v32, 0x48, v198
	v_lshl_add_u32 v32, v32, 1, v66
	v_add_u32_e32 v197, 0x12000, v32
	v_add_u32_e32 v200, 0x1b000, v32

.LBB0_1505:
	s_cmp_lt_i32 s88, 17
	s_cselect_b64 s[4:5], -1, 0
	s_and_b64 s[6:7], s[4:5], s[8:9]
	s_andn2_b64 vcc, exec, s[6:7]
	s_cbranch_vccnz .LBB0_1514
	s_cmpk_gt_i32 s2, 0xff
	s_cbranch_scc1 .LBB0_1514
	s_add_u32 s14, s34, 0x28c4000
	s_addc_u32 s15, s35, 0
	s_add_u32 s33, s34, 0x2320000
	s_waitcnt lgkmcnt(0)
	s_addc_u32 s60, s35, 0
	s_lshl_b32 s6, s2, 5
	s_and_b32 s6, s6, 0xe0
	s_ashr_i32 s7, s2, 3
	s_add_i32 s6, s6, s7
	s_ashr_i32 s78, s6, 7
	s_lshl_b32 s6, s6, 6
	s_and_b32 s80, s6, 0x1f00
	s_lshl_b32 s6, s7, 8
	v_mov_b32_e32 v76, v204
	s_and_b32 s79, s6, 0x300
	s_mul_i32 s6, s80, 0x1600
	s_add_u32 s6, s14, s6
	v_ashrrev_i32_e32 v77, 3, v76
	s_waitcnt vmcnt(7)
	v_lshlrev_b32_e32 v0, 3, v76
	s_movk_i32 s8, 0xb00
	v_and_b32_e32 v78, 56, v0
	s_addc_u32 s7, s15, 0
	s_mul_i32 s10, s78, 0xb00
	v_mul_lo_u32 v0, v77, s8
	s_mul_hi_i32 s9, s78, 0xb00
	s_add_u32 s56, s6, s10
	v_or_b32_e32 v0, v0, v78
	v_mov_b32_e32 v199, 0
	s_addc_u32 s57, s7, s9
	v_lshlrev_b32_e32 v196, 1, v0
	v_mov_b32_e32 v197, v199
	v_lshl_add_u64 v[0:1], s[56:57], 0, v[196:197]
	s_mov_b32 s61, 0x58000
	s_mul_i32 s6, s79, 0x1600
	v_add_co_u32_e32 v64, vcc, s61, v0
	s_add_u32 s6, s33, s6
	s_nop 0
	v_addc_co_u32_e32 v65, vcc, 0, v1, vcc
	s_mov_b32 s62, 0xb0000
	s_addc_u32 s7, s60, 0
	v_add_co_u32_e32 v66, vcc, s62, v0
	s_add_u32 s58, s6, s10
	s_nop 0
	v_addc_co_u32_e32 v67, vcc, 0, v1, vcc
	s_mov_b32 s63, 0x108000
	s_addc_u32 s59, s7, s9
	v_add_co_u32_e32 v68, vcc, s63, v0
	global_load_dwordx4 v[32:35], v196, s[56:57]
	global_load_dwordx4 v[48:51], v196, s[58:59]
	v_addc_co_u32_e32 v69, vcc, 0, v1, vcc
	v_lshl_add_u64 v[0:1], s[58:59], 0, v[196:197]
	v_add_co_u32_e32 v70, vcc, s61, v0
	global_load_dwordx4 v[36:39], v[64:65], off
	global_load_dwordx4 v[40:43], v[66:67], off
	v_addc_co_u32_e32 v71, vcc, 0, v1, vcc
	v_add_co_u32_e32 v72, vcc, s62, v0
	global_load_dwordx4 v[44:47], v[68:69], off
	global_load_dwordx4 v[52:55], v[70:71], off
	v_addc_co_u32_e32 v73, vcc, 0, v1, vcc
	v_add_co_u32_e32 v74, vcc, s63, v0
	global_load_dwordx4 v[56:59], v[72:73], off
	s_nop 0
	v_addc_co_u32_e32 v75, vcc, 0, v1, vcc
	global_load_dwordx4 v[60:63], v[74:75], off
	global_load_dwordx4 v[4:7], v196, s[56:57] offset:128
	global_load_dwordx4 v[8:11], v[64:65], off offset:128
	global_load_dwordx4 v[12:15], v[66:67], off offset:128
	global_load_dwordx4 v[16:19], v[68:69], off offset:128
	global_load_dwordx4 v[0:3], v196, s[58:59] offset:128
	global_load_dwordx4 v[20:23], v[70:71], off offset:128
	global_load_dwordx4 v[24:27], v[72:73], off offset:128
	global_load_dwordx4 v[28:31], v[74:75], off offset:128
	s_movk_i32 s6, 0x90
	v_ashrrev_i32_e32 v65, 1, v76
	v_mul_lo_u32 v66, v77, s6
	v_bfe_u32 v64, v76, 4, 2
	v_and_b32_e32 v65, 0xffffff80, v65
	v_lshl_add_u32 v202, v78, 1, v66
	v_lshrrev_b32_e32 v158, 3, v76
	v_lshrrev_b32_e32 v159, 1, v158
	v_xor_b32_e32 v158, v158, v159
	v_bfe_u32 v158, v158, 2, 1
	v_and_b32_e32 v159, v158, v76
	v_lshlrev_b32_e32 v159, 5, v159
	v_lshlrev_b32_e32 v158, 4, v158
	v_sub_u32_e32 v158, v158, v159
	v_add_u32_e32 v202, v202, v158
	v_add_u32_e32 v206, 0x12000, v202
	v_and_b32_e32 v207, 0xcf, v76
	s_mov_b64 s[96:97], s[92:93]
	v_lshl_or_b32 v203, v64, 2, v65
	v_add_u32_e32 v208, 0x1b000, v202
	s_mov_b32 s64, 0x18000
	s_mov_b64 s[8:9], 0x19000
	s_mov_b32 s65, 0x19000
	s_mov_b64 s[10:11], 0x19800
	s_mov_b64 s[12:13], 0x20000
	s_mov_b32 s66, 0x20000
	s_mov_b64 s[16:17], 0x20800
	s_mov_b64 s[18:19], 0x21000
	s_mov_b32 s67, 0x21000
	s_mov_b64 s[20:21], 0x21800
	s_mov_b64 s[22:23], 0x28000
	s_mov_b32 s68, 0x28000
	s_mov_b64 s[24:25], 0x28800
	s_mov_b64 s[26:27], 0x29000
	s_waitcnt vmcnt(15)
	ds_write_b128 v202, v[32:35]
	s_waitcnt vmcnt(13)
	ds_write_b128 v202, v[36:39] offset:9216
	s_waitcnt vmcnt(12)
	ds_write_b128 v202, v[40:43] offset:18432
	s_waitcnt vmcnt(11)
	ds_write_b128 v202, v[44:47] offset:27648
	ds_write_b128 v206, v[48:51]
	s_waitcnt vmcnt(10)
	ds_write_b128 v206, v[52:55] offset:9216
	s_waitcnt vmcnt(9)
	ds_write_b128 v206, v[56:59] offset:18432
	s_waitcnt vmcnt(8)
	ds_write_b128 v206, v[60:63] offset:27648
	v_and_or_b32 v33, v76, 15, v65
	v_lshlrev_b32_e32 v32, 4, v64
	v_lshrrev_b32_e32 v159, 1, v76
	v_xor_b32_e32 v158, v76, v159
	v_bfe_u32 v158, v158, 2, 1
	v_bfe_u32 v159, v76, 4, 1
	v_and_b32_e32 v159, v159, v158
	v_lshlrev_b32_e32 v159, 5, v159
	v_lshlrev_b32_e32 v158, 4, v158
	v_sub_u32_e32 v158, v158, v159
	v_add_u32_e32 v32, v32, v158
	v_mad_u64_u32 v[200:201], s[6:7], v33, s6, v[32:33]
	v_mul_u32_u24_e32 v33, 0x48, v207
	v_lshl_add_u32 v32, v33, 1, v32
	v_add_u32_e32 v201, 0x12000, v32
	v_add_u32_e32 v209, 0x1b000, v32
	s_mov_b64 s[6:7], 0x18800
	s_mov_b32 s69, 0x29000
	s_mov_b64 s[28:29], 0x29800
	s_mov_b64 s[30:31], 0x30000
	s_mov_b32 s70, 0x30000
	s_mov_b64 s[36:37], 0x30800
	s_mov_b64 s[38:39], 0x31000
	s_mov_b32 s71, 0x31000
	s_mov_b64 s[40:41], 0x31800
	s_mov_b64 s[42:43], 0x38000
	s_mov_b32 s72, 0x38000
	s_mov_b64 s[44:45], 0x38800
	s_mov_b64 s[46:47], 0x39000
	s_mov_b32 s73, 0x39000
	s_mov_b64 s[48:49], 0x39800
	s_mov_b32 s74, s2
	s_mov_b64 s[50:51], s[56:57]
	s_mov_b64 s[52:53], s[58:59]
	s_waitcnt lgkmcnt(0)
	s_barrier
